# attention first half: the first PV group's 8 V-fragment LDS reads issued right after the last QK^T MFMA, so their latency hides under the P cvt/permlane block and the V global loads
# speedup vs baseline: 1.0122x; 1.0007x over previous
.LBB0_561:
	ds_read_b128 v[64:67], v189 offset:49152
	ds_read_b128 v[68:71], v189 offset:57344
	ds_read_b128 v[210:213], v190 offset:49152
	ds_read_b128 v[218:221], v190 offset:57344
	s_add_i32 s0, 0, 0x12000
	s_waitcnt lgkmcnt(3)
	v_mfma_f32_32x32x16_bf16 v[80:95], v[64:67], v[120:123], 0
	v_xor_b32_e32 v241, v243, v158
	s_add_u32 s100, s64, 0x34e80000
	s_addc_u32 s101, s65, 0
	s_lshl_b32 m0, s33, 4
	s_add_i32 m0, m0, 0x8000
	s_nop 0
	global_load_lds_dwordx4 v241, s[100:101]
	s_add_u32 s100, s64, 0x34ea0000
	s_addc_u32 s101, s65, 0
	s_add_i32 m0, m0, 0x2000
	s_nop 0
	global_load_lds_dwordx4 v241, s[100:101]
	v_xor_b32_e32 v241, v242, v170
	s_add_u32 s100, s64, 0x1ea04000
	s_addc_u32 s101, s65, 0
	s_add_i32 m0, m0, 0x6000
	s_nop 0
	global_load_lds_dwordx4 v241, s[100:101]
	v_exp_f32_e32 v175, v175
	v_exp_f32_e32 v217, v217
	v_add_f32_e32 v148, 0, v175
	s_waitcnt lgkmcnt(2)
	v_mfma_f32_32x32x16_bf16 v[64:79], v[68:71], v[120:123], 0
	v_exp_f32_e32 v149, v149
	v_add_f32_e32 v148, v217, v148
	v_exp_f32_e32 v216, v216
	s_waitcnt lgkmcnt(1)
	v_mfma_f32_32x32x16_bf16 v[80:95], v[210:213], v[124:127], v[80:95]
	v_add_f32_e32 v148, v149, v148
	v_exp_f32_e32 v150, v150
	v_add_f32_e32 v148, v216, v148
	s_waitcnt lgkmcnt(0)
	v_mfma_f32_32x32x16_bf16 v[64:79], v[218:221], v[124:127], v[64:79]
	ds_read_b128 v[210:213], v191 offset:49152
	ds_read_b128 v[218:221], v191 offset:57344
	v_exp_f32_e32 v174, v174
	v_add_f32_e32 v148, v150, v148
	v_exp_f32_e32 v151, v151
	v_add_f32_e32 v148, v174, v148
	s_waitcnt lgkmcnt(1)
	v_mfma_f32_32x32x16_bf16 v[80:95], v[210:213], v[116:119], v[80:95]
	v_exp_f32_e32 v173, v173
	v_add_f32_e32 v148, v151, v148
	v_exp_f32_e32 v154, v154
	s_waitcnt lgkmcnt(0)
	v_mfma_f32_32x32x16_bf16 v[64:79], v[218:221], v[116:119], v[64:79]
	ds_read_b128 v[210:213], v192 offset:49152
	ds_read_b128 v[218:221], v192 offset:57344
	v_add_f32_e32 v148, v173, v148
	v_exp_f32_e32 v172, v172
	v_add_f32_e32 v148, v154, v148
	s_waitcnt lgkmcnt(1)
	v_mfma_f32_32x32x16_bf16 v[80:95], v[210:213], v[112:115], v[80:95]
	v_exp_f32_e32 v153, v153
	v_add_f32_e32 v148, v172, v148
	v_exp_f32_e32 v155, v155
	v_add_f32_e32 v148, v153, v148
	s_waitcnt lgkmcnt(0)
	v_mfma_f32_32x32x16_bf16 v[64:79], v[218:221], v[112:115], v[64:79]
	ds_read_b128 v[210:213], v193 offset:49152
	ds_read_b128 v[218:221], v193 offset:57344
	ds_read_b128 v[232:235], v194 offset:49152
	ds_read_b128 v[236:239], v194 offset:57344
	v_exp_f32_e32 v145, v145
	v_add_f32_e32 v148, v155, v148
	v_exp_f32_e32 v140, v140
	s_waitcnt lgkmcnt(3)
	v_mfma_f32_32x32x16_bf16 v[80:95], v[210:213], v[108:111], v[80:95]
	v_exp_f32_e32 v147, v147
	v_add_f32_e32 v148, v145, v148
	v_exp_f32_e32 v141, v141
	s_waitcnt lgkmcnt(2)
	v_mfma_f32_32x32x16_bf16 v[64:79], v[218:221], v[108:111], v[64:79]
	ds_read_b128 v[210:213], v195 offset:49152
	ds_read_b128 v[218:221], v195 offset:57344
	v_exp_f32_e32 v144, v144
	v_add_f32_e32 v148, v147, v148
	v_exp_f32_e32 v138, v138
	v_exp_f32_e32 v146, v146
	s_waitcnt lgkmcnt(3)
	v_mfma_f32_32x32x16_bf16 v[80:95], v[232:235], v[104:107], v[80:95]
	v_add_f32_e32 v148, v144, v148
	v_exp_f32_e32 v139, v139
	v_add_f32_e32 v148, v146, v148
	s_waitcnt lgkmcnt(2)
	v_mfma_f32_32x32x16_bf16 v[64:79], v[236:239], v[104:107], v[64:79]
	ds_read_b128 v[232:235], v196 offset:49152
	ds_read_b128 v[236:239], v196 offset:57344
	v_exp_f32_e32 v132, v132
	v_add_f32_e32 v148, v140, v148
	v_exp_f32_e32 v133, v133
	s_waitcnt lgkmcnt(3)
	v_mfma_f32_32x32x16_bf16 v[80:95], v[210:213], v[100:103], v[80:95]
	v_add_u32_e32 v230, s0, v198
	v_add_u32_e32 v231, s0, v200
	v_add_f32_e32 v148, v141, v148
	v_exp_f32_e32 v130, v130
	v_add_f32_e32 v148, v138, v148
	v_exp_f32_e32 v131, v131
	s_waitcnt lgkmcnt(2)
	v_mfma_f32_32x32x16_bf16 v[64:79], v[218:221], v[100:103], v[64:79]
	ds_read_b128 v[210:213], v230
	ds_read_b128 v[218:221], v230 offset:4096
	ds_read_b128 v[222:225], v197
	v_add_f32_e32 v148, v139, v148
	v_exp_f32_e32 v128, v128
	v_add_f32_e32 v148, v132, v148
	s_waitcnt lgkmcnt(4)
	v_mfma_f32_32x32x16_bf16 v[80:95], v[232:235], v[96:99], v[80:95]
	v_exp_f32_e32 v129, v129
	v_add_f32_e32 v148, v133, v148
	v_exp_f32_e32 v142, v142
	s_waitcnt lgkmcnt(3)
	v_mfma_f32_32x32x16_bf16 v[64:79], v[236:239], v[96:99], v[64:79]
	ds_read_b128 v[232:235], v231
	ds_read_b128 v[236:239], v231 offset:4096
	ds_read_b128 v[226:229], v184
	v_add_f32_e32 v148, v130, v148
	v_exp_f32_e32 v143, v143
	v_add_f32_e32 v148, v131, v148
	v_exp_f32_e32 v136, v136
	s_waitcnt lgkmcnt(3)
	v_mfma_f32_32x32x16_bf16 v[80:95], v[210:213], v[222:225], v[80:95]
	v_add_f32_e32 v148, v128, v148
	v_exp_f32_e32 v137, v137
	v_add_f32_e32 v148, v129, v148
	v_mfma_f32_32x32x16_bf16 v[64:79], v[218:221], v[222:225], v[64:79]
	v_add_u32_e32 v244, s0, v202
	v_add_u32_e32 v247, s0, v204
	ds_read_b128 v[210:213], v244
	ds_read_b128 v[218:221], v244 offset:4096
	ds_read_b128 v[222:225], v183
	v_exp_f32_e32 v134, v134
	v_add_f32_e32 v148, v142, v148
	v_exp_f32_e32 v135, v135
	s_waitcnt lgkmcnt(3)
	v_mfma_f32_32x32x16_bf16 v[80:95], v[232:235], v[226:229], v[80:95]
	v_add_f32_e32 v148, v143, v148
	v_add_f32_e32 v148, v136, v148
	v_add_f32_e32 v148, v137, v148
	v_add_f32_e32 v148, v134, v148
	v_add_f32_e32 v214, v135, v148
	v_mov_b32_e32 v215, v214
	s_nop 1
	v_permlane32_swap_b32_e32 v214, v215
	v_mfma_f32_32x32x16_bf16 v[64:79], v[236:239], v[226:229], v[64:79]
	ds_read_b128 v[232:235], v247
	ds_read_b128 v[236:239], v247 offset:4096
	ds_read_b128 v[226:229], v182
	s_waitcnt lgkmcnt(3)
	v_mfma_f32_32x32x16_bf16 v[80:95], v[210:213], v[222:225], v[80:95]
	v_mfma_f32_32x32x16_bf16 v[64:79], v[218:221], v[222:225], v[64:79]
	v_cvt_pk_bf16_f32 v148, v175, v217
	v_cvt_pk_bf16_f32 v149, v149, v216
	v_cvt_pk_bf16_f32 v150, v150, v174
	v_cvt_pk_bf16_f32 v151, v151, v173
	v_cvt_pk_bf16_f32 v152, v154, v172
	v_cvt_pk_bf16_f32 v153, v153, v155
	s_waitcnt lgkmcnt(0)
	v_mfma_f32_32x32x16_bf16 v[80:95], v[232:235], v[226:229], v[80:95]
	v_cvt_pk_bf16_f32 v154, v145, v147
	v_permlane32_swap_b32_e32 v148, v150
	v_cvt_pk_bf16_f32 v155, v144, v146
	v_permlane32_swap_b32_e32 v152, v154
	v_cvt_pk_bf16_f32 v216, v140, v141
	v_mfma_f32_32x32x16_bf16 v[64:79], v[236:239], v[226:229], v[64:79]
	ds_read_b64_tr_b16 v[224:225], v181 offset:0
	ds_read_b64_tr_b16 v[226:227], v181 offset:0x800
	ds_read_b64_tr_b16 v[228:229], v181 offset:0x1000
	ds_read_b64_tr_b16 v[230:231], v181 offset:0x1800
	ds_read_b64_tr_b16 v[232:233], v181 offset:0x2000
	ds_read_b64_tr_b16 v[234:235], v181 offset:0x2800
	ds_read_b64_tr_b16 v[236:237], v181 offset:0x3000
	ds_read_b64_tr_b16 v[238:239], v181 offset:0x3800
	v_cvt_pk_bf16_f32 v217, v138, v139
	v_cvt_pk_bf16_f32 v218, v132, v133
	v_cvt_pk_bf16_f32 v219, v130, v131
	v_cvt_pk_bf16_f32 v220, v128, v129
	v_cvt_pk_bf16_f32 v221, v142, v143
	v_cvt_pk_bf16_f32 v222, v136, v137
	v_cvt_pk_bf16_f32 v223, v134, v135
	v_permlane32_swap_b32_e32 v149, v151
	v_permlane32_swap_b32_e32 v153, v155
	v_permlane32_swap_b32_e32 v216, v218
	v_permlane32_swap_b32_e32 v217, v219
	v_permlane32_swap_b32_e32 v220, v222
	v_permlane32_swap_b32_e32 v221, v223
	v_lshl_add_u64 v[172:173], s[64:65], 0, v[158:159]
	s_mov_b32 s0, 0x34e80000
	v_add_co_u32_e32 v132, vcc, s0, v172
	s_mov_b32 s0, 0x34ea0000
	s_nop 0
	v_addc_co_u32_e32 v133, vcc, 0, v173, vcc
	v_add_co_u32_e32 v136, vcc, s0, v172
	v_lshl_add_u64 v[174:175], s[64:65], 0, v[170:171]
	s_nop 0
	v_addc_co_u32_e32 v137, vcc, 0, v173, vcc
	global_load_dwordx4 v[128:131], v[132:133], off offset:256
	s_nop 0
	s_nop 0
	global_load_dwordx4 v[140:143], v[136:137], off offset:256
	s_nop 0
	s_mov_b32 s0, 0x1ea04000
	s_nop 0
	s_waitcnt lgkmcnt(6)
	v_mfma_f32_32x32x16_bf16 v[0:15], v[148:151], v[224:227], v[0:15]
	ds_read_b64_tr_b16 v[224:225], v181 offset:0x200
	ds_read_b64_tr_b16 v[226:227], v181 offset:0xa00
	s_waitcnt lgkmcnt(6)
	v_mfma_f32_32x32x16_bf16 v[0:15], v[152:155], v[228:231], v[0:15]
	ds_read_b64_tr_b16 v[228:229], v181 offset:0x1200
	ds_read_b64_tr_b16 v[230:231], v181 offset:0x1a00
	s_waitcnt lgkmcnt(6)
	v_mfma_f32_32x32x16_bf16 v[0:15], v[216:219], v[232:235], v[0:15]
	ds_read_b64_tr_b16 v[232:233], v181 offset:0x2200
	ds_read_b64_tr_b16 v[234:235], v181 offset:0x2a00
	s_waitcnt lgkmcnt(6)
	v_mfma_f32_32x32x16_bf16 v[0:15], v[220:223], v[236:239], v[0:15]
	ds_read_b64_tr_b16 v[236:237], v181 offset:0x3200
	ds_read_b64_tr_b16 v[238:239], v181 offset:0x3a00
	s_waitcnt lgkmcnt(6)
	v_mfma_f32_32x32x16_bf16 v[48:63], v[148:151], v[224:227], v[48:63]
	ds_read_b64_tr_b16 v[224:225], v181 offset:0x400
	ds_read_b64_tr_b16 v[226:227], v181 offset:0xc00
	s_waitcnt lgkmcnt(6)
	v_mfma_f32_32x32x16_bf16 v[48:63], v[152:155], v[228:231], v[48:63]
	ds_read_b64_tr_b16 v[228:229], v181 offset:0x1400
	ds_read_b64_tr_b16 v[230:231], v181 offset:0x1c00
	s_waitcnt lgkmcnt(6)
	v_mfma_f32_32x32x16_bf16 v[48:63], v[216:219], v[232:235], v[48:63]
	ds_read_b64_tr_b16 v[232:233], v181 offset:0x2400
	ds_read_b64_tr_b16 v[234:235], v181 offset:0x2c00
	s_waitcnt lgkmcnt(6)
	v_mfma_f32_32x32x16_bf16 v[48:63], v[220:223], v[236:239], v[48:63]
	ds_read_b64_tr_b16 v[236:237], v181 offset:0x3400
	ds_read_b64_tr_b16 v[238:239], v181 offset:0x3c00
	s_waitcnt lgkmcnt(6)
	v_mfma_f32_32x32x16_bf16 v[32:47], v[148:151], v[224:227], v[32:47]
	ds_read_b64_tr_b16 v[224:225], v181 offset:0x600
	ds_read_b64_tr_b16 v[226:227], v181 offset:0xe00
	s_waitcnt lgkmcnt(6)
	v_mfma_f32_32x32x16_bf16 v[32:47], v[152:155], v[228:231], v[32:47]
	ds_read_b64_tr_b16 v[228:229], v181 offset:0x1600
	ds_read_b64_tr_b16 v[230:231], v181 offset:0x1e00
	s_waitcnt lgkmcnt(6)
	v_mfma_f32_32x32x16_bf16 v[32:47], v[216:219], v[232:235], v[32:47]
	ds_read_b64_tr_b16 v[232:233], v181 offset:0x2600
	ds_read_b64_tr_b16 v[234:235], v181 offset:0x2e00
	s_waitcnt lgkmcnt(6)
	v_mfma_f32_32x32x16_bf16 v[32:47], v[220:223], v[236:239], v[32:47]
	ds_read_b64_tr_b16 v[236:237], v181 offset:0x3600
	ds_read_b64_tr_b16 v[238:239], v181 offset:0x3e00
	s_waitcnt lgkmcnt(6)
	v_mfma_f32_32x32x16_bf16 v[16:31], v[148:151], v[224:227], v[16:31]
	v_max_f32_e32 v148, v81, v81
	v_max_f32_e32 v149, v80, v80
	v_max_f32_e32 v148, v149, v148
	v_max3_f32 v148, v148, v82, v83
	v_max3_f32 v148, v148, v84, v85
	v_max3_f32 v148, v148, v86, v87
	v_max3_f32 v148, v148, v88, v89
	v_max3_f32 v148, v148, v90, v91
	v_max3_f32 v148, v148, v92, v93
	s_waitcnt lgkmcnt(4)
	v_mfma_f32_32x32x16_bf16 v[16:31], v[152:155], v[228:231], v[16:31]
	v_max3_f32 v148, v148, v94, v95
	v_max3_f32 v148, v148, v64, v65
	v_max3_f32 v148, v148, v66, v67
	v_max3_f32 v148, v148, v68, v69
	v_max3_f32 v148, v148, v70, v71
	v_max3_f32 v148, v148, v72, v73
	v_max3_f32 v148, v148, v74, v75
	v_max3_f32 v148, v148, v76, v77
	s_waitcnt lgkmcnt(2)
	v_mfma_f32_32x32x16_bf16 v[16:31], v[216:219], v[232:235], v[16:31]
	v_max3_f32 v148, v148, v78, v79
	v_mov_b32_e32 v149, v148
	s_nop 1
	v_permlane32_swap_b32_e32 v148, v149
	v_max_f32_e32 v149, v149, v149
	v_max_f32_e32 v148, v148, v148
	v_max_f32_e32 v148, v148, v149
	v_sub_f32_e32 v149, v148, v209
	v_cmp_ge_f32_e32 vcc, s90, v149
	v_max_f32_e32 v149, v209, v209
	v_max_f32_e32 v148, v149, v148
	s_waitcnt lgkmcnt(0)
	v_mfma_f32_32x32x16_bf16 v[16:31], v[220:223], v[236:239], v[16:31]
	v_sub_f32_e32 v149, v209, v148
	v_mul_f32_e32 v149, 0x3dd53b94, v149
	v_exp_f32_e32 v149, v149
	s_cmp_eq_u64 vcc, exec
	s_cselect_b64 s[6:7], -1, 0
	s_barrier
	s_waitcnt vmcnt(0)
	v_cndmask_b32_e64 v152, v149, 1.0, s[6:7]
	s_waitcnt vmcnt(4)
	ds_write_b128 v185, v[128:131]
	s_waitcnt vmcnt(2)
	ds_write_b128 v186, v[140:143]
	s_waitcnt vmcnt(1)
	v_add_u32_e32 v128, 0x10000, v207
	v_cmp_gt_f32_e32 vcc, 1.0, v152
	s_waitcnt vmcnt(0)
	s_cbranch_vccz .LBB0_565
	s_and_saveexec_b64 s[0:1], s[4:5]
	ds_write_b32 v178, v152 offset:128
	s_or_b64 exec, exec, s[0:1]
	s_waitcnt lgkmcnt(0)
	v_add_u32_e32 v140, v157, v160
	ds_read_b128 v[128:131], v140 offset:224
	ds_read_b128 v[132:135], v140 offset:192
	ds_read_b128 v[136:139], v140 offset:160
	ds_read_b128 v[140:143], v140 offset:128
	s_waitcnt lgkmcnt(3)
	v_pk_mul_f32 v[12:13], v[12:13], v[128:129]
	s_waitcnt lgkmcnt(2)
	v_pk_mul_f32 v[8:9], v[8:9], v[132:133]
	s_waitcnt lgkmcnt(1)
	v_pk_mul_f32 v[4:5], v[4:5], v[136:137]
	v_pk_mul_f32 v[14:15], v[14:15], v[130:131]
	v_pk_mul_f32 v[10:11], v[10:11], v[134:135]
	v_pk_mul_f32 v[6:7], v[6:7], v[138:139]
	s_waitcnt lgkmcnt(0)
	v_pk_mul_f32 v[2:3], v[2:3], v[142:143]
	v_pk_mul_f32 v[0:1], v[0:1], v[140:141]
	v_pk_mul_f32 v[60:61], v[60:61], v[128:129]
	v_pk_mul_f32 v[56:57], v[56:57], v[132:133]
	v_pk_mul_f32 v[52:53], v[52:53], v[136:137]
	v_pk_mul_f32 v[62:63], v[62:63], v[130:131]
	v_pk_mul_f32 v[58:59], v[58:59], v[134:135]
	v_pk_mul_f32 v[54:55], v[54:55], v[138:139]
	v_pk_mul_f32 v[50:51], v[50:51], v[142:143]
	v_pk_mul_f32 v[48:49], v[48:49], v[140:141]
	v_pk_mul_f32 v[44:45], v[44:45], v[128:129]
	v_pk_mul_f32 v[40:41], v[40:41], v[132:133]
	v_pk_mul_f32 v[36:37], v[36:37], v[136:137]
	v_pk_mul_f32 v[46:47], v[46:47], v[130:131]
	v_pk_mul_f32 v[42:43], v[42:43], v[134:135]
	v_pk_mul_f32 v[38:39], v[38:39], v[138:139]
	v_pk_mul_f32 v[34:35], v[34:35], v[142:143]
	v_pk_mul_f32 v[32:33], v[32:33], v[140:141]
	v_pk_mul_f32 v[28:29], v[28:29], v[128:129]
	v_pk_mul_f32 v[24:25], v[24:25], v[132:133]
	v_pk_mul_f32 v[20:21], v[20:21], v[136:137]
	v_pk_mul_f32 v[30:31], v[30:31], v[130:131]
	v_pk_mul_f32 v[26:27], v[26:27], v[134:135]
	v_pk_mul_f32 v[22:23], v[22:23], v[138:139]
	v_pk_mul_f32 v[18:19], v[18:19], v[142:143]
	v_pk_mul_f32 v[16:17], v[16:17], v[140:141]
